# ml_local: three tile loads issued ahead of the gate-prefix barrier (on top of conversion de-serialization)
# speedup vs baseline: 1.0042x; 1.0042x over previous
; __device__ __forceinline__ bf16_t f2bf(float f) { return (bf16_t)(cvt_pk_bf16(f, 0.f) & 0xffffu); }
; __device__ __forceinline__ float bfs2f(short b) { return __uint_as_float(((unsigned)(unsigned short)b) << 16); }
; __device__ __forceinline__ void ml_local(LAS unsigned char* L, const bf16_t* Z, const float* GATES, bf16_t* MLC, float* MLDN, float* MLG, float* MLA) {
;     ...
;         { const int i = tid >> 3, sg = tid & 7; const int s = 64 * j + i, t = g ? (S_ - 1 - s) : s; const bf16_t* zr = Z + ((size_t)b * S_ + t) * 2560;
;             const bf16x8 kv = *(const bf16x8*)(zr + 256 + h * 64 + sg * 8);
; #pragma unroll
;             for (int e = 0; e < 8; ++e) Kt[(sg * 8 + e) * 72 + i] = (bf16_t)kv[e];
;             const float w = wst[i];
; #pragma unroll
;             for (int hh = 0; hh < 2; ++hh) { const bf16x8 vv = *(const bf16x8*)(zr + 512 + h * 128 + (sg + 8 * hh) * 8);
; #pragma unroll
;                 for (int e = 0; e < 8; ++e) Vt[((sg + 8 * hh) * 8 + e) * 72 + i] = f2bf(bfs2f(vv[e]) * w); } }
;         __syncthreads();
.LBB0_514:
	s_or_b64 exec, exec, s[24:25]
	v_add_u32_e32 v11, s6, v14
	s_cmpk_lt_u32 s20, 0x800
	s_cselect_b64 s[54:55], -1, 0
	v_sub_u32_e32 v12, 0x3fff, v11
	v_readlane_b32 s2, v251, 26
	v_cndmask_b32_e64 v11, v12, v11, s[54:55]
	v_readlane_b32 s3, v251, 27
	v_lshl_add_u32 v11, s5, 14, v11
	s_lshl_b32 s28, s4, 7
	v_mov_b64_e32 v[12:13], s[2:3]
	s_movk_i32 s2, 0x1400
	v_mad_i64_i32 v[22:23], s[6:7], v11, s2, v[12:13]
	v_lshl_add_u64 v[12:13], v[22:23], 0, s[28:29]
	v_mov_b32_e32 v11, v0
	v_lshl_add_u64 v[12:13], v[12:13], 0, v[10:11]
	global_load_dwordx4 v[104:107], v[12:13], off offset:512
	s_lshl_b32 s28, s4, 8
	v_lshl_add_u64 v[102:103], v[22:23], 0, s[28:29]
	v_lshl_add_u64 v[102:103], v[102:103], 0, v[10:11]
	global_load_dwordx4 v[108:111], v[102:103], off offset:1024
	global_load_dwordx4 v[112:115], v[102:103], off offset:1152
	s_waitcnt lgkmcnt(0)
	s_barrier
	s_lshl_b32 s28, s4, 8
	s_waitcnt vmcnt(2)
	v_mov_b32_e32 v18, v104
	v_mov_b32_e32 v19, v105
	v_mov_b32_e32 v20, v106
	v_mov_b32_e32 v21, v107
	ds_write_b16 v3, v18
	ds_write_b16_d16_hi v3, v18 offset:144
	ds_write_b16 v3, v19 offset:288
	ds_write_b16_d16_hi v3, v19 offset:432
	ds_write_b16 v3, v20 offset:576
	ds_write_b16_d16_hi v3, v20 offset:720
	ds_write_b16 v3, v21 offset:864
	ds_write_b16_d16_hi v3, v21 offset:1008
	v_lshl_add_u64 v[18:19], v[22:23], 0, s[28:29]
	v_lshl_add_u64 v[22:23], v[18:19], 0, v[10:11]
	s_waitcnt vmcnt(1)
	v_mov_b32_e32 v18, v108
	v_mov_b32_e32 v19, v109
	v_mov_b32_e32 v20, v110
	v_mov_b32_e32 v21, v111
	ds_read_b32 v12, v15 offset:27648
	s_waitcnt vmcnt(0)
	v_lshlrev_b32_e32 v11, 16, v18
	s_waitcnt lgkmcnt(0)
	v_mul_f32_e32 v11, v12, v11
	v_cvt_pk_bf16_f32 v11, v11, s0
	ds_write_b16 v3, v11 offset:9216
	v_and_b32_e32 v11, 0xffff0000, v18
	v_mul_f32_e32 v11, v12, v11
	v_cvt_pk_bf16_f32 v11, v11, s0
	ds_write_b16 v3, v11 offset:9360
	v_lshlrev_b32_e32 v11, 16, v19
	v_mul_f32_e32 v11, v12, v11
	v_cvt_pk_bf16_f32 v11, v11, s0
	ds_write_b16 v3, v11 offset:9504
	v_and_b32_e32 v11, 0xffff0000, v19
	v_mul_f32_e32 v11, v12, v11
	v_cvt_pk_bf16_f32 v11, v11, s0
	ds_write_b16 v3, v11 offset:9648
	v_lshlrev_b32_e32 v11, 16, v20
	v_mul_f32_e32 v11, v12, v11
	v_cvt_pk_bf16_f32 v11, v11, s0
	ds_write_b16 v3, v11 offset:9792
	v_and_b32_e32 v11, 0xffff0000, v20
	v_mul_f32_e32 v11, v12, v11
	v_cvt_pk_bf16_f32 v11, v11, s0
	ds_write_b16 v3, v11 offset:9936
	v_lshlrev_b32_e32 v11, 16, v21
	v_mul_f32_e32 v11, v12, v11
	v_cvt_pk_bf16_f32 v11, v11, s0
	ds_write_b16 v3, v11 offset:10080
	v_and_b32_e32 v11, 0xffff0000, v21
	v_mov_b32_e32 v18, v112
	v_mov_b32_e32 v19, v113
	v_mov_b32_e32 v20, v114
	v_mov_b32_e32 v21, v115
	v_mul_f32_e32 v11, v12, v11
	v_cvt_pk_bf16_f32 v11, v11, s0
	ds_write_b16 v3, v11 offset:10224
	s_waitcnt vmcnt(0)
	v_lshlrev_b32_e32 v11, 16, v18
	v_mul_f32_e32 v11, v12, v11
	v_cvt_pk_bf16_f32 v11, v11, s0
	ds_write_b16 v3, v11 offset:18432
	v_and_b32_e32 v11, 0xffff0000, v18
	v_mul_f32_e32 v11, v12, v11
	v_cvt_pk_bf16_f32 v11, v11, s0
	ds_write_b16 v3, v11 offset:18576
	v_lshlrev_b32_e32 v11, 16, v19
	v_mul_f32_e32 v11, v12, v11
	v_cvt_pk_bf16_f32 v11, v11, s0
	ds_write_b16 v3, v11 offset:18720
	v_and_b32_e32 v11, 0xffff0000, v19
	v_mul_f32_e32 v11, v12, v11
	v_cvt_pk_bf16_f32 v11, v11, s0
	ds_write_b16 v3, v11 offset:18864
	v_lshlrev_b32_e32 v11, 16, v20
	v_mul_f32_e32 v11, v12, v11
	v_cvt_pk_bf16_f32 v11, v11, s0
	ds_write_b16 v3, v11 offset:19008
	v_and_b32_e32 v11, 0xffff0000, v20
	v_mul_f32_e32 v11, v12, v11
	v_cvt_pk_bf16_f32 v11, v11, s0
	ds_write_b16 v3, v11 offset:19152
	v_lshlrev_b32_e32 v11, 16, v21
	v_mul_f32_e32 v11, v12, v11
	v_cvt_pk_bf16_f32 v11, v11, s0
	ds_write_b16 v3, v11 offset:19296
	v_and_b32_e32 v11, 0xffff0000, v21
	v_mul_f32_e32 v11, v12, v11
	v_cvt_pk_bf16_f32 v11, v11, s0
	ds_write_b16 v3, v11 offset:19440
	s_waitcnt lgkmcnt(0)
	s_barrier
	s_and_saveexec_b64 s[4:5], s[42:43]
	s_xor_b64 s[24:25], exec, s[4:5]
	s_ashr_i32 s21, s20, 31
	s_or_saveexec_b64 s[24:25], s[24:25]
	v_mov_b64_e32 v[12:13], s[20:21]
	s_xor_b64 exec, exec, s[24:25]
	s_cbranch_execz .LBB0_510
; __device__ __forceinline__ float bf2f(bf16_t b) { return __uint_as_float(((unsigned)b) << 16); }
; __device__ __forceinline__ void ml_local(LAS unsigned char* L, const bf16_t* Z, const float* GATES, bf16_t* MLC, float* MLDN, float* MLG, float* MLA) {
;     ...
;         if (tid < 64) { float s = 0.f; for (int i = 0; i < 64; ++i) s += wst[i] * bf2f(Kt[tid * 72 + i]); MLDN[(size_t)item * 64 + tid] = s; }
	ds_read_b128 v[18:21], v0 offset:27648
	ds_read_b128 v[22:25], v0 offset:27664
	ds_read_b128 v[26:29], v16
	ds_read_b128 v[30:33], v0 offset:27680
	ds_read_b128 v[34:37], v0 offset:27696
	ds_read_b128 v[38:41], v16 offset:16
	ds_read_b128 v[42:45], v16 offset:32
	ds_read_b128 v[46:49], v16 offset:48
	s_waitcnt lgkmcnt(5)
	v_lshlrev_b32_e32 v11, 16, v26
	v_fma_f32 v11, v18, v11, 0
	v_and_b32_e32 v12, 0xffff0000, v26
	v_fmac_f32_e32 v11, v19, v12
	v_lshlrev_b32_e32 v12, 16, v27
	v_fmac_f32_e32 v11, v20, v12
	v_and_b32_e32 v12, 0xffff0000, v27
	v_fmac_f32_e32 v11, v21, v12
	v_lshlrev_b32_e32 v12, 16, v28
	v_fmac_f32_e32 v11, v22, v12
	v_and_b32_e32 v12, 0xffff0000, v28
	v_fmac_f32_e32 v11, v23, v12
	v_lshlrev_b32_e32 v12, 16, v29
	v_fmac_f32_e32 v11, v24, v12
	v_and_b32_e32 v12, 0xffff0000, v29
	v_fmac_f32_e32 v11, v25, v12
	s_waitcnt lgkmcnt(2)
	v_lshlrev_b32_e32 v12, 16, v38
	v_fmac_f32_e32 v11, v30, v12
	v_and_b32_e32 v12, 0xffff0000, v38
	v_fmac_f32_e32 v11, v31, v12
	v_lshlrev_b32_e32 v12, 16, v39
	v_fmac_f32_e32 v11, v32, v12
	v_and_b32_e32 v12, 0xffff0000, v39
	v_fmac_f32_e32 v11, v33, v12
	v_lshlrev_b32_e32 v12, 16, v40
	ds_read_b128 v[18:21], v0 offset:27712
	ds_read_b128 v[22:25], v0 offset:27728
	v_fmac_f32_e32 v11, v34, v12
	v_and_b32_e32 v12, 0xffff0000, v40
	v_fmac_f32_e32 v11, v35, v12
	v_lshlrev_b32_e32 v12, 16, v41
	v_fmac_f32_e32 v11, v36, v12
	v_and_b32_e32 v12, 0xffff0000, v41
	v_fmac_f32_e32 v11, v37, v12
	s_waitcnt lgkmcnt(3)
	v_lshlrev_b32_e32 v12, 16, v42
	s_waitcnt lgkmcnt(1)
	v_fmac_f32_e32 v11, v18, v12
	v_and_b32_e32 v12, 0xffff0000, v42
	v_fmac_f32_e32 v11, v19, v12
	v_lshlrev_b32_e32 v12, 16, v43
	v_fmac_f32_e32 v11, v20, v12
	v_and_b32_e32 v12, 0xffff0000, v43
	v_fmac_f32_e32 v11, v21, v12
	v_lshlrev_b32_e32 v12, 16, v44
	ds_read_b128 v[18:21], v0 offset:27744
	s_waitcnt lgkmcnt(1)
	v_fmac_f32_e32 v11, v22, v12
	v_and_b32_e32 v12, 0xffff0000, v44
	v_fmac_f32_e32 v11, v23, v12
	v_lshlrev_b32_e32 v12, 16, v45
	v_fmac_f32_e32 v11, v24, v12
	v_and_b32_e32 v12, 0xffff0000, v45
	v_fmac_f32_e32 v11, v25, v12
	v_lshlrev_b32_e32 v12, 16, v46
	ds_read_b128 v[22:25], v0 offset:27760
	s_waitcnt lgkmcnt(1)
	v_fmac_f32_e32 v11, v18, v12
	v_and_b32_e32 v12, 0xffff0000, v46
	v_fmac_f32_e32 v11, v19, v12
	v_lshlrev_b32_e32 v12, 16, v47
	v_fmac_f32_e32 v11, v20, v12
	v_and_b32_e32 v12, 0xffff0000, v47
	v_fmac_f32_e32 v11, v21, v12
	ds_read_b128 v[18:21], v16 offset:64
	v_lshlrev_b32_e32 v12, 16, v48
	ds_read_b128 v[26:29], v0 offset:27776
	ds_read_b128 v[30:33], v0 offset:27792
	s_waitcnt lgkmcnt(3)
	v_fmac_f32_e32 v11, v22, v12
	v_and_b32_e32 v12, 0xffff0000, v48
	v_fmac_f32_e32 v11, v23, v12
	v_lshlrev_b32_e32 v12, 16, v49
	v_fmac_f32_e32 v11, v24, v12
	v_and_b32_e32 v12, 0xffff0000, v49
	v_fmac_f32_e32 v11, v25, v12
	ds_read_b128 v[22:25], v16 offset:80
	s_waitcnt lgkmcnt(3)
	v_lshlrev_b32_e32 v12, 16, v18
	s_waitcnt lgkmcnt(2)
	v_fmac_f32_e32 v11, v26, v12
	v_and_b32_e32 v12, 0xffff0000, v18
	v_fmac_f32_e32 v11, v27, v12
	v_lshlrev_b32_e32 v12, 16, v19
	v_fmac_f32_e32 v11, v28, v12
	v_and_b32_e32 v12, 0xffff0000, v19
	v_fmac_f32_e32 v11, v29, v12
	v_lshlrev_b32_e32 v12, 16, v20
	ds_read_b128 v[26:29], v0 offset:27808
	s_waitcnt lgkmcnt(2)
	v_fmac_f32_e32 v11, v30, v12
	v_and_b32_e32 v12, 0xffff0000, v20
	v_fmac_f32_e32 v11, v31, v12
	v_lshlrev_b32_e32 v12, 16, v21
	v_fmac_f32_e32 v11, v32, v12
	v_and_b32_e32 v12, 0xffff0000, v21
	v_fmac_f32_e32 v11, v33, v12
	s_waitcnt lgkmcnt(1)
	v_lshlrev_b32_e32 v12, 16, v22
	ds_read_b128 v[18:21], v0 offset:27824
	s_waitcnt lgkmcnt(1)
	v_fmac_f32_e32 v11, v26, v12
	v_and_b32_e32 v12, 0xffff0000, v22
	v_fmac_f32_e32 v11, v27, v12
	v_lshlrev_b32_e32 v12, 16, v23
	v_fmac_f32_e32 v11, v28, v12
	v_and_b32_e32 v12, 0xffff0000, v23
	v_fmac_f32_e32 v11, v29, v12
	v_lshlrev_b32_e32 v12, 16, v24
	s_waitcnt lgkmcnt(0)
	v_fmac_f32_e32 v11, v18, v12
	v_and_b32_e32 v12, 0xffff0000, v24
	v_fmac_f32_e32 v11, v19, v12
	v_lshlrev_b32_e32 v12, 16, v25
	ds_read_b128 v[26:29], v16 offset:96
	v_fmac_f32_e32 v11, v20, v12
	v_and_b32_e32 v12, 0xffff0000, v25
	ds_read_b128 v[22:25], v0 offset:27840
	ds_read_b128 v[30:33], v0 offset:27856
	v_fmac_f32_e32 v11, v21, v12
	ds_read_b128 v[18:21], v16 offset:112
	s_waitcnt lgkmcnt(3)
	v_lshlrev_b32_e32 v12, 16, v26
	s_waitcnt lgkmcnt(2)
	v_fmac_f32_e32 v11, v22, v12
	v_and_b32_e32 v12, 0xffff0000, v26
	v_fmac_f32_e32 v11, v23, v12
	v_lshlrev_b32_e32 v12, 16, v27
	v_fmac_f32_e32 v11, v24, v12
	v_and_b32_e32 v12, 0xffff0000, v27
	v_fmac_f32_e32 v11, v25, v12
	v_and_b32_e32 v13, 0xffff0000, v28
	v_lshlrev_b32_e32 v12, 16, v28
	s_waitcnt lgkmcnt(1)
	v_pk_mul_f32 v[12:13], v[30:31], v[12:13]
	ds_read_b128 v[22:25], v0 offset:27872
	v_add_f32_e32 v11, v11, v12
	v_add_f32_e32 v11, v11, v13
	v_and_b32_e32 v13, 0xffff0000, v29
	v_lshlrev_b32_e32 v12, 16, v29
	v_pk_mul_f32 v[12:13], v[32:33], v[12:13]
	ds_read_b128 v[26:29], v0 offset:27888
	v_add_f32_e32 v11, v11, v12
	v_add_f32_e32 v11, v11, v13
	s_waitcnt lgkmcnt(2)
	v_and_b32_e32 v13, 0xffff0000, v18
	v_lshlrev_b32_e32 v12, 16, v18
	s_waitcnt lgkmcnt(1)
	v_pk_mul_f32 v[12:13], v[22:23], v[12:13]
	s_ashr_i32 s21, s20, 31
	v_add_f32_e32 v11, v11, v12
	v_add_f32_e32 v11, v11, v13
	v_and_b32_e32 v13, 0xffff0000, v19
	v_lshlrev_b32_e32 v12, 16, v19
	v_pk_mul_f32 v[12:13], v[24:25], v[12:13]
	s_lshl_b64 s[4:5], s[20:21], 8
	v_add_f32_e32 v11, v11, v12
	v_add_f32_e32 v11, v11, v13
	v_and_b32_e32 v13, 0xffff0000, v20
	v_lshlrev_b32_e32 v12, 16, v20
	s_waitcnt lgkmcnt(0)
	v_pk_mul_f32 v[12:13], v[26:27], v[12:13]
	s_nop 0
	v_add_f32_e32 v11, v11, v12
	v_add_f32_e32 v11, v11, v13
	v_and_b32_e32 v13, 0xffff0000, v21
	v_lshlrev_b32_e32 v12, 16, v21
	v_pk_mul_f32 v[12:13], v[28:29], v[12:13]
	s_nop 0
	v_add_f32_e32 v11, v11, v12
	v_add_f32_e32 v11, v11, v13
	v_lshl_add_u64 v[12:13], v[4:5], 0, s[4:5]
	global_store_dword v[12:13], v11, off
	v_mov_b64_e32 v[12:13], s[20:21]
	s_branch .LBB0_510
